# cross-attention queue: next ticket fetched at the start of the unit epilogue; dispatch barrier no longer drains VMEM
# speedup vs baseline: 1.0032x; 1.0009x over previous
; #define CASE(k) if (PH_ON(k) && ph_lo <= (k) && (k) < ph_hi)
; __global__ void __launch_bounds__(512, 2) mega(Params p) {
;     ...
;         CASE(9) {
;             unsigned* ctr = (unsigned*)(ws + O_CTR) + 16 + 4 * rep9;
;             constexpr int NU_P = 16 * 4 * 16, NU_S = 32 * 4;
;             for (;;) {
;                 int u = queue_next(ctr, lds);
.LBB0_1320:
	s_cmp_lt_i32 s54, 10
	s_cselect_b64 s[0:1], -1, 0
	s_cmp_gt_i32 s55, 9
	s_cselect_b64 s[4:5], -1, 0
	s_and_b64 s[0:1], s[0:1], s[4:5]
	s_andn2_b64 vcc, exec, s[0:1]
	s_cbranch_vccnz .LBB0_1399
	s_add_u32 s6, s52, 0xf621000
	s_addc_u32 s7, s53, 0
	s_add_u32 s8, s52, 0x1b3a1000
	s_addc_u32 s9, s53, 0
	s_add_u32 s10, s52, 0x1cba1000
	s_addc_u32 s11, s53, 0
	s_add_u32 s12, s52, 0x13821000
	s_addc_u32 s13, s53, 0
	s_add_i32 s0, 0, 0x23f00
	v_mbcnt_lo_u32_b32 v0, -1, 0
	v_mov_b32_e32 v217, 1
	s_mov_b32 s15, 0
	v_mov_b32_e32 v220, s0
	s_movk_i32 s1, 0x47f
	v_mov_b32_e32 v1, 0
	s_movk_i32 s4, 0x210
	s_movk_i32 s5, 0x240
	v_mbcnt_hi_u32_b32 v221, -1, v0
	s_mov_b64 s[16:17], exec
	v_readlane_b32 s18, v252, 6
	v_readlane_b32 s19, v252, 7
	s_and_b64 s[18:19], s[16:17], s[18:19]
	s_mov_b64 exec, s[18:19]
	s_cbranch_execz .Lq9_init_done
	v_mov_b32_e32 v251, 0
	global_atomic_add v250, v251, v217, s[52:53] offset:64 sc0
	s_waitcnt vmcnt(0)
.Lq9_init_done:
	s_mov_b64 exec, s[16:17]
	s_branch .LBB0_1324

; #define LAS __attribute__((address_space(3)))
; __device__ __forceinline__ int queue_next(unsigned* ctr, LAS unsigned char* lds) {
;     volatile LAS unsigned* w = (volatile LAS unsigned*)(lds + LDS_CTL);
;     if (threadIdx.x == 0) w[0] = atomicAdd(ctr, 1u);
;     __syncthreads();
;     const int u = (int)w[0];
;     __syncthreads();
;     return u;
; }
.LBB0_1324:
	s_waitcnt lgkmcnt(0)
	s_mov_b64 s[16:17], exec
	v_readlane_b32 s18, v252, 6
	v_readlane_b32 s19, v252, 7
	s_and_b64 s[18:19], s[16:17], s[18:19]
	s_mov_b64 exec, s[18:19]
	s_cbranch_execz .LBB0_1326
	s_waitcnt vmcnt(16)
	v_mov_b32_e32 v2, s0
	ds_write_b32 v2, v250
.LBB0_1326:
	s_or_b64 exec, exec, s[16:17]
	s_waitcnt lgkmcnt(0)
	s_barrier
	ds_read_b32 v0, v220
	s_mov_b64 s[16:17], -1
	s_waitcnt lgkmcnt(0)
	s_barrier
	v_cmp_lt_i32_e32 vcc, s1, v0
	v_readfirstlane_b32 s20, v0
	s_cbranch_vccnz .LBB0_1323
	s_cmpk_gt_i32 s20, 0x3ff
	s_cbranch_scc0 .LBB0_1338
	s_add_u32 s98, s52, 0x2fb46800
	s_addc_u32 s99, s53, 0
	s_mov_b32 s101, 0
	v_mov_b32_e32 v250, 0

; #define GASP __attribute__((address_space(1)))
; __device__ __forceinline__ float frcp(float x) { return __builtin_amdgcn_rcpf(x); }
; __device__ __forceinline__ void cross_unit(const Params& p, LAS unsigned char* L, int bb, int h, int qi) {
;     ...
;     if (active) {
;         l += __shfl_xor(l, 32);
;         const float inv = frcp(l);
;         bf16_t* op = (bf16_t*)(ws + O_OC) + (size_t)(rowq0 + sub * 32 + r) * D + h * 256 + dh * 128 + 4 * hi;
; #pragma unroll
;         for (int eb = 0; eb < 4; ++eb)
; #pragma unroll
;             for (int g4 = 0; g4 < 4; ++g4) { u32x2 w; w.x = pk2(OT[eb][4 * g4] * inv, OT[eb][4 * g4 + 1] * inv); w.y = pk2(OT[eb][4 * g4 + 2] * inv, OT[eb][4 * g4 + 3] * inv);
;                 *(GASP u32x2*)(op + eb * 32 + 8 * g4) = w; }
;     }
.LBB0_1351:
	s_and_b64 vcc, exec, s[16:17]
	s_cbranch_vccz .LBB0_1322
	s_mov_b64 s[100:101], exec
	v_cmp_eq_u32_e64 s[98:99], 0, v208
	s_and_b64 s[98:99], s[100:101], s[98:99]
	s_mov_b64 exec, s[98:99]
	s_cbranch_execz .Lq9_pf_done
	v_mov_b32_e32 v251, 0
	global_atomic_add v250, v251, v217, s[52:53] offset:64 sc0
.Lq9_pf_done:
	s_mov_b64 exec, s[100:101]
	s_waitcnt lgkmcnt(0)
	v_add_f32_e32 v0, v213, v0
	v_rcp_f32_e32 v0, v0
	v_ashrrev_i32_e32 v2, 1, v2
	v_lshl_add_u64 v[4:5], s[12:13], 0, v[210:211]
	v_and_b32_e32 v2, 0xffffff80, v2
	v_lshl_add_u64 v[4:5], s[14:15], 1, v[4:5]
	v_ashrrev_i32_e32 v3, 31, v2
	v_lshl_add_u64 v[2:3], v[2:3], 1, v[4:5]
	v_mov_b32_e32 v213, v1
	v_pk_mul_f32 v[4:5], v[64:65], v[0:1] op_sel_hi:[1,0]
	s_waitcnt vmcnt(4)
	v_pk_mul_f32 v[6:7], v[66:67], v[0:1] op_sel_hi:[1,0]
	v_lshl_add_u64 v[2:3], v[212:213], 1, v[2:3]
	v_cvt_pk_bf16_f32 v4, v4, v5
	v_cvt_pk_bf16_f32 v5, v6, v7
	global_store_dwordx2 v[2:3], v[4:5], off
	v_pk_mul_f32 v[4:5], v[68:69], v[0:1] op_sel_hi:[1,0]
	v_pk_mul_f32 v[6:7], v[70:71], v[0:1] op_sel_hi:[1,0]
	v_cvt_pk_bf16_f32 v4, v4, v5
	v_cvt_pk_bf16_f32 v5, v6, v7
	global_store_dwordx2 v[2:3], v[4:5], off offset:16
	v_pk_mul_f32 v[4:5], v[72:73], v[0:1] op_sel_hi:[1,0]
	v_pk_mul_f32 v[6:7], v[74:75], v[0:1] op_sel_hi:[1,0]
	v_cvt_pk_bf16_f32 v4, v4, v5
	v_cvt_pk_bf16_f32 v5, v6, v7
	global_store_dwordx2 v[2:3], v[4:5], off offset:32
	v_pk_mul_f32 v[4:5], v[76:77], v[0:1] op_sel_hi:[1,0]
	v_pk_mul_f32 v[6:7], v[78:79], v[0:1] op_sel_hi:[1,0]
	v_cvt_pk_bf16_f32 v4, v4, v5
	v_cvt_pk_bf16_f32 v5, v6, v7
	global_store_dwordx2 v[2:3], v[4:5], off offset:48
	v_pk_mul_f32 v[4:5], v[48:49], v[0:1] op_sel_hi:[1,0]
	v_pk_mul_f32 v[6:7], v[50:51], v[0:1] op_sel_hi:[1,0]
	v_cvt_pk_bf16_f32 v4, v4, v5
	v_cvt_pk_bf16_f32 v5, v6, v7
	global_store_dwordx2 v[2:3], v[4:5], off offset:64
	v_pk_mul_f32 v[4:5], v[52:53], v[0:1] op_sel_hi:[1,0]
	v_pk_mul_f32 v[6:7], v[54:55], v[0:1] op_sel_hi:[1,0]
	v_cvt_pk_bf16_f32 v4, v4, v5
	v_cvt_pk_bf16_f32 v5, v6, v7
	global_store_dwordx2 v[2:3], v[4:5], off offset:80
	v_pk_mul_f32 v[4:5], v[56:57], v[0:1] op_sel_hi:[1,0]
	v_pk_mul_f32 v[6:7], v[58:59], v[0:1] op_sel_hi:[1,0]
	v_cvt_pk_bf16_f32 v4, v4, v5
	v_cvt_pk_bf16_f32 v5, v6, v7
	global_store_dwordx2 v[2:3], v[4:5], off offset:96
	v_pk_mul_f32 v[4:5], v[60:61], v[0:1] op_sel_hi:[1,0]
	v_pk_mul_f32 v[6:7], v[62:63], v[0:1] op_sel_hi:[1,0]
	v_cvt_pk_bf16_f32 v4, v4, v5
	v_cvt_pk_bf16_f32 v5, v6, v7
	global_store_dwordx2 v[2:3], v[4:5], off offset:112
	v_pk_mul_f32 v[4:5], v[32:33], v[0:1] op_sel_hi:[1,0]
	v_pk_mul_f32 v[6:7], v[34:35], v[0:1] op_sel_hi:[1,0]
	v_cvt_pk_bf16_f32 v4, v4, v5
	v_cvt_pk_bf16_f32 v5, v6, v7
	global_store_dwordx2 v[2:3], v[4:5], off offset:128
	v_pk_mul_f32 v[4:5], v[36:37], v[0:1] op_sel_hi:[1,0]
	v_pk_mul_f32 v[6:7], v[38:39], v[0:1] op_sel_hi:[1,0]
	v_cvt_pk_bf16_f32 v4, v4, v5
	v_cvt_pk_bf16_f32 v5, v6, v7
	global_store_dwordx2 v[2:3], v[4:5], off offset:144
	v_pk_mul_f32 v[4:5], v[40:41], v[0:1] op_sel_hi:[1,0]
	v_pk_mul_f32 v[6:7], v[42:43], v[0:1] op_sel_hi:[1,0]
	v_cvt_pk_bf16_f32 v4, v4, v5
	v_cvt_pk_bf16_f32 v5, v6, v7
	global_store_dwordx2 v[2:3], v[4:5], off offset:160
	v_pk_mul_f32 v[4:5], v[44:45], v[0:1] op_sel_hi:[1,0]
	v_pk_mul_f32 v[6:7], v[46:47], v[0:1] op_sel_hi:[1,0]
	v_cvt_pk_bf16_f32 v4, v4, v5
	v_cvt_pk_bf16_f32 v5, v6, v7
	global_store_dwordx2 v[2:3], v[4:5], off offset:176
	v_pk_mul_f32 v[4:5], v[16:17], v[0:1] op_sel_hi:[1,0]
	v_pk_mul_f32 v[6:7], v[18:19], v[0:1] op_sel_hi:[1,0]
	v_cvt_pk_bf16_f32 v4, v4, v5
	v_cvt_pk_bf16_f32 v5, v6, v7
	global_store_dwordx2 v[2:3], v[4:5], off offset:192
	v_pk_mul_f32 v[4:5], v[20:21], v[0:1] op_sel_hi:[1,0]
	v_pk_mul_f32 v[6:7], v[22:23], v[0:1] op_sel_hi:[1,0]
	v_cvt_pk_bf16_f32 v4, v4, v5
	v_cvt_pk_bf16_f32 v5, v6, v7
	global_store_dwordx2 v[2:3], v[4:5], off offset:208
	v_pk_mul_f32 v[4:5], v[24:25], v[0:1] op_sel_hi:[1,0]
	v_pk_mul_f32 v[6:7], v[26:27], v[0:1] op_sel_hi:[1,0]
	v_cvt_pk_bf16_f32 v4, v4, v5
	v_cvt_pk_bf16_f32 v5, v6, v7
	global_store_dwordx2 v[2:3], v[4:5], off offset:224
	v_pk_mul_f32 v[4:5], v[28:29], v[0:1] op_sel_hi:[1,0]
	v_pk_mul_f32 v[6:7], v[30:31], v[0:1] op_sel_hi:[1,0]
	v_cvt_pk_bf16_f32 v4, v4, v5
	v_cvt_pk_bf16_f32 v5, v6, v7
	global_store_dwordx2 v[2:3], v[4:5], off offset:240
	s_branch .LBB0_1322
